# sample attention: K (f32 cache -> bf16) and V^T tile staging loads issued together per key tile instead of nine serial load-wait-store round trips
# speedup vs baseline: 1.0108x; 1.0033x over previous
; DI unsigned pk2(float lo, float hi) { const hwf2_t v = {lo, hi}; const hwbf2_t b = __builtin_convertvector(v, hwbf2_t); return __builtin_bit_cast(unsigned, b); }
; template <int DK, int DV, int KT, bool SAMPLE>
; DI void attn_item(CP c, int l, int qb, int h, unsigned char* sm) {
;     ...
;         } else {
;             const int k0 = kt * 32;
;             for (int v = gt; v < 32 * 40; v += 256) { const int key = v / 40, s = v % 40, kk = k0 + key; u32x4 o = (u32x4){0u, 0u, 0u, 0u};
;                 if (kk < 2048) { const float* src = s < 32 ? c->in[I_CLAT] + ((size_t)(l * 32 + b) * 2048 + kk) * 256 + s * 8 : c->in[I_CKPE] + ((size_t)(l * 32 + b) * 2048 + kk) * 64 + (s - 32) * 8;
;                     const f32x4 a = *(const f32x4*)src, bq = *(const f32x4*)(src + 4); o.x = pk2(a[0], a[1]); o.y = pk2(a[2], a[3]); o.z = pk2(bq[0], bq[1]); o.w = pk2(bq[2], bq[3]); }
;                 else if (kk < 2064) { const int rr = MP + b * 16 + (kk - 2048); o = *(const u32x4*)(s < 32 ? LATg + (size_t)rr * 256 + s * 8 : KPEg + (size_t)rr * 64 + (s - 32) * 8); }
;                 *(u32x4*)(Ks + key * QS + s * 8) = o; }
;             for (int v = gt; v < 256 * 4; v += 256) { const int dv = v >> 2, s = v & 3; u32x4 o = (u32x4){0u, 0u, 0u, 0u};
;                 if (k0 < LTS) o = *(const u32x4*)(LTg + ((size_t)b * 256 + dv) * LTS + k0 + s * 8);
;                 *(u32x4*)(Vs + dv * VS + s * 8) = o; }
.LBB0_715:
	s_waitcnt lgkmcnt(0)
	s_barrier
	v_lshl_add_u32 v6, s14, 6, v182
	s_nop 1
	v_readfirstlane_b32 s32, v6
	s_nop 1
	s_cmpk_lt_u32 s32, 0x800
	s_cbranch_scc0 .Lmla_slow
	s_load_dwordx2 s[98:99], s[46:47], 0x10
	s_load_dwordx2 s[100:101], s[46:47], 0x18
	s_mov_b32 s16, 0xcccd
	s_waitcnt lgkmcnt(0)
	s_sub_u32 s88, s100, s98
	s_subb_u32 s89, s101, s99
	v_mov_b32_e32 v246, s88
	v_mov_b32_e32 v247, s89
	v_add_u32_e32 v7, 0x0, v180
	v_mul_u32_u24_e32 v0, s16, v7
	v_lshrrev_b32_e32 v10, 21, v0
	v_mul_u32_u24_e32 v0, 40, v10
	v_sub_u32_e32 v11, v7, v0
	v_add_u32_e32 v8, v6, v10
	v_mul_u32_u24_e32 v0, 0x290, v10
	v_lshlrev_b32_e32 v2, 4, v11
	v_add3_u32 v156, v181, v0, v2
	v_cmp_lt_u32_e64 s[40:41], 31, v11
	v_lshlrev_b32_e32 v0, 10, v8
	v_lshlrev_b32_e32 v2, 8, v8
	v_add_u32_e32 v2, 0xfffffc00, v2
	v_cndmask_b32_e64 v0, v0, v2, s[40:41]
	v_lshl_add_u32 v0, v11, 5, v0
	v_cndmask_b32_e64 v2, v166, v164, s[40:41]
	v_cndmask_b32_e64 v3, v167, v165, s[40:41]
	v_lshl_add_u64 v[2:3], v[2:3], 0, v[0:1]
	v_cndmask_b32_e64 v10, 0, v246, s[40:41]
	v_cndmask_b32_e64 v11, 0, v247, s[40:41]
	v_lshl_add_u64 v[2:3], v[2:3], 0, v[10:11]
	v_lshl_add_u64 v[2:3], v[2:3], 0, s[98:99]
	global_load_dwordx4 v[222:225], v[2:3], off
	global_load_dwordx4 v[226:229], v[2:3], off offset:16
	v_add_u32_e32 v7, 0x100, v180
	v_mul_u32_u24_e32 v0, s16, v7
	v_lshrrev_b32_e32 v10, 21, v0
	v_mul_u32_u24_e32 v0, 40, v10
	v_sub_u32_e32 v11, v7, v0
	v_add_u32_e32 v8, v6, v10
	v_mul_u32_u24_e32 v0, 0x290, v10
	v_lshlrev_b32_e32 v2, 4, v11
	v_add3_u32 v158, v181, v0, v2
	v_cmp_lt_u32_e64 s[40:41], 31, v11
	v_lshlrev_b32_e32 v0, 10, v8
	v_lshlrev_b32_e32 v2, 8, v8
	v_add_u32_e32 v2, 0xfffffc00, v2
	v_cndmask_b32_e64 v0, v0, v2, s[40:41]
	v_lshl_add_u32 v0, v11, 5, v0
	v_cndmask_b32_e64 v2, v166, v164, s[40:41]
	v_cndmask_b32_e64 v3, v167, v165, s[40:41]
	v_lshl_add_u64 v[2:3], v[2:3], 0, v[0:1]
	v_cndmask_b32_e64 v10, 0, v246, s[40:41]
	v_cndmask_b32_e64 v11, 0, v247, s[40:41]
	v_lshl_add_u64 v[2:3], v[2:3], 0, v[10:11]
	v_lshl_add_u64 v[2:3], v[2:3], 0, s[98:99]
	global_load_dwordx4 v[230:233], v[2:3], off
	global_load_dwordx4 v[234:237], v[2:3], off offset:16
	v_add_u32_e32 v7, 0x200, v180
	v_mul_u32_u24_e32 v0, s16, v7
	v_lshrrev_b32_e32 v10, 21, v0
	v_mul_u32_u24_e32 v0, 40, v10
	v_sub_u32_e32 v11, v7, v0
	v_add_u32_e32 v8, v6, v10
	v_mul_u32_u24_e32 v0, 0x290, v10
	v_lshlrev_b32_e32 v2, 4, v11
	v_add3_u32 v159, v181, v0, v2
	v_cmp_lt_u32_e64 s[40:41], 31, v11
	v_lshlrev_b32_e32 v0, 10, v8
	v_lshlrev_b32_e32 v2, 8, v8
	v_add_u32_e32 v2, 0xfffffc00, v2
	v_cndmask_b32_e64 v0, v0, v2, s[40:41]
	v_lshl_add_u32 v0, v11, 5, v0
	v_cndmask_b32_e64 v2, v166, v164, s[40:41]
	v_cndmask_b32_e64 v3, v167, v165, s[40:41]
	v_lshl_add_u64 v[2:3], v[2:3], 0, v[0:1]
	v_cndmask_b32_e64 v10, 0, v246, s[40:41]
	v_cndmask_b32_e64 v11, 0, v247, s[40:41]
	v_lshl_add_u64 v[2:3], v[2:3], 0, v[10:11]
	v_lshl_add_u64 v[2:3], v[2:3], 0, s[98:99]
	global_load_dwordx4 v[238:241], v[2:3], off
	global_load_dwordx4 v[242:245], v[2:3], off offset:16
	v_add_u32_e32 v7, 0x300, v180
	v_mul_u32_u24_e32 v0, s16, v7
	v_lshrrev_b32_e32 v10, 21, v0
	v_mul_u32_u24_e32 v0, 40, v10
	v_sub_u32_e32 v11, v7, v0
	v_add_u32_e32 v8, v6, v10
	v_mul_u32_u24_e32 v0, 0x290, v10
	v_lshlrev_b32_e32 v2, 4, v11
	v_add3_u32 v192, v181, v0, v2
	v_cmp_lt_u32_e64 s[40:41], 31, v11
	v_lshlrev_b32_e32 v0, 10, v8
	v_lshlrev_b32_e32 v2, 8, v8
	v_add_u32_e32 v2, 0xfffffc00, v2
	v_cndmask_b32_e64 v0, v0, v2, s[40:41]
	v_lshl_add_u32 v0, v11, 5, v0
	v_cndmask_b32_e64 v2, v166, v164, s[40:41]
	v_cndmask_b32_e64 v3, v167, v165, s[40:41]
	v_lshl_add_u64 v[2:3], v[2:3], 0, v[0:1]
	v_cndmask_b32_e64 v10, 0, v246, s[40:41]
	v_cndmask_b32_e64 v11, 0, v247, s[40:41]
	v_lshl_add_u64 v[2:3], v[2:3], 0, v[10:11]
	v_lshl_add_u64 v[2:3], v[2:3], 0, s[98:99]
	global_load_dwordx4 v[204:207], v[2:3], off
	global_load_dwordx4 v[148:151], v[2:3], off offset:16
	v_add_u32_e32 v7, 0x400, v180
	v_mul_u32_u24_e32 v0, s16, v7
	v_lshrrev_b32_e32 v10, 21, v0
	v_mul_u32_u24_e32 v0, 40, v10
	v_sub_u32_e32 v11, v7, v0
	v_add_u32_e32 v8, v6, v10
	v_mul_u32_u24_e32 v0, 0x290, v10
	v_lshlrev_b32_e32 v2, 4, v11
	v_add3_u32 v193, v181, v0, v2
	v_cmp_lt_u32_e64 s[40:41], 31, v11
	v_lshlrev_b32_e32 v0, 10, v8
	v_lshlrev_b32_e32 v2, 8, v8
	v_add_u32_e32 v2, 0xfffffc00, v2
	v_cndmask_b32_e64 v0, v0, v2, s[40:41]
	v_lshl_add_u32 v0, v11, 5, v0
	v_cndmask_b32_e64 v2, v166, v164, s[40:41]
	v_cndmask_b32_e64 v3, v167, v165, s[40:41]
	v_lshl_add_u64 v[2:3], v[2:3], 0, v[0:1]
	v_cndmask_b32_e64 v10, 0, v246, s[40:41]
	v_cndmask_b32_e64 v11, 0, v247, s[40:41]
	v_lshl_add_u64 v[2:3], v[2:3], 0, v[10:11]
	v_lshl_add_u64 v[2:3], v[2:3], 0, s[98:99]
	global_load_dwordx4 v[152:155], v[2:3], off
	global_load_dwordx4 v[144:147], v[2:3], off offset:16
	v_ashrrev_i32_e32 v7, 31, v6
	v_lshl_add_u64 v[8:9], v[6:7], 1, v[172:173]
	v_mov_b32_e32 v0, v213
	v_lshl_add_u64 v[2:3], v[0:1], 1, v[8:9]
	global_load_dwordx4 v[12:15], v[2:3], off
	s_waitcnt vmcnt(9)
	v_cvt_pk_bf16_f32 v222, v222, v223
	v_cvt_pk_bf16_f32 v223, v224, v225
	v_cvt_pk_bf16_f32 v224, v226, v227
	v_cvt_pk_bf16_f32 v225, v228, v229
	ds_write_b128 v156, v[222:225] offset:41984
	v_add_u32_e32 v0, 0x21000, v213
	v_lshl_add_u64 v[2:3], v[0:1], 1, v[8:9]
	global_load_dwordx4 v[226:229], v[2:3], off
	s_waitcnt vmcnt(8)
	v_cvt_pk_bf16_f32 v230, v230, v231
	v_cvt_pk_bf16_f32 v231, v232, v233
	v_cvt_pk_bf16_f32 v232, v234, v235
	v_cvt_pk_bf16_f32 v233, v236, v237
	ds_write_b128 v158, v[230:233] offset:41984
	v_add_u32_e32 v0, 0x42000, v213
	v_lshl_add_u64 v[2:3], v[0:1], 1, v[8:9]
	global_load_dwordx4 v[234:237], v[2:3], off
	s_waitcnt vmcnt(7)
	v_cvt_pk_bf16_f32 v238, v238, v239
	v_cvt_pk_bf16_f32 v239, v240, v241
	v_cvt_pk_bf16_f32 v240, v242, v243
	v_cvt_pk_bf16_f32 v241, v244, v245
	ds_write_b128 v159, v[238:241] offset:41984
	v_add_u32_e32 v0, 0x63000, v213
	v_lshl_add_u64 v[2:3], v[0:1], 1, v[8:9]
	global_load_dwordx4 v[242:245], v[2:3], off
	s_waitcnt vmcnt(6)
	v_cvt_pk_bf16_f32 v204, v204, v205
	v_cvt_pk_bf16_f32 v205, v206, v207
	v_cvt_pk_bf16_f32 v206, v148, v149
	v_cvt_pk_bf16_f32 v207, v150, v151
	ds_write_b128 v192, v[204:207] offset:41984
	s_waitcnt vmcnt(4)
	v_cvt_pk_bf16_f32 v152, v152, v153
	v_cvt_pk_bf16_f32 v153, v154, v155
	v_cvt_pk_bf16_f32 v154, v144, v145
	v_cvt_pk_bf16_f32 v155, v146, v147
	ds_write_b128 v193, v[152:155] offset:41984
	s_waitcnt vmcnt(3)
	ds_write_b128 v214, v[12:15] offset:0
	s_waitcnt vmcnt(2)
	ds_write_b128 v214, v[226:229] offset:5120
	s_waitcnt vmcnt(1)
	ds_write_b128 v214, v[234:237] offset:10240
	s_waitcnt vmcnt(0)
	ds_write_b128 v214, v[242:245] offset:15360
	s_mov_b64 s[12:13], 0
	s_branch .LBB0_735
.Lmla_slow:
	s_mov_b64 s[12:13], 0
	v_mov_b32_e32 v7, v180
	s_branch .LBB0_718
